# P1+P9 stagger: WGs with one tile fewer sleep ~17us at the GEMM start so epilogue bursts interleave
# baseline (speedup 1.0000x reference)
; __global__ void __launch_bounds__(512, 2) fwd(Params P) {
;     ...
;     if (IN(9)) for (int rep_ = 0; rep_ < NREP(9); ++rep_) { pg8::Gemm g{(const bf16_t*)(ws + O_X1B), (const bf16_t*)(ws + O_WGUT), MP, 2 * DFF, D}; pg8::StaticOrder S; S.init(MP, 2 * DFF, gridDim.x, blockIdx.x);
.LBB0_1138:
	s_cmp_lt_i32 s14, 10
	s_cselect_b64 s[0:1], -1, 0
	s_cmp_gt_i32 s15, 9
	s_cselect_b64 s[2:3], -1, 0
	s_and_b64 s[0:1], s[0:1], s[2:3]
	s_andn2_b64 vcc, exec, s[0:1]
	s_cbranch_vccnz .LBB0_1319
	s_cmpk_lt_u32 s94, 0xac
	s_cbranch_scc1 .Lstag9_done
	s_movk_i32 s0, 5

; #define LAS __attribute__((address_space(3)))
; #define PG8_STAGE(bufoff, gbase, voff) do { _Pragma("unroll") for (int _i = 0; _i < 2; ++_i) \
;         __builtin_amdgcn_global_load_lds((const unsigned*)((const char*)(gbase) + (voff)[_i]), (LAS unsigned*)(lds + (bufoff) + ldsw + _i * 8192), 16, 0, 0); } while (0)
; #define PG8_WAIT_V(n) asm volatile("s_waitcnt vmcnt(" #n ")" ::: "memory")
; #define PG8_BAR __builtin_amdgcn_s_barrier()
; template <class Epi>
; __device__ __forceinline__ void gemm_phase(LAS unsigned char* lds, const Gemm g, const StaticOrder& S, const Epi& E) {
;     const int tid = threadIdx.x, wid = __builtin_amdgcn_readfirstlane(tid >> 6), lane = tid & 63, wr = wid >> 2, wc = wid & 3, fr = lane & 15, fq = lane >> 4;
;     const int K = g.K, nt = K / BK;
;     unsigned voffA[2], voffB[2];
; #pragma unroll
;     for (int i = 0; i < 2; ++i) { int R, C; stage_rc(tid * 16 + i * 8192, R, C); const int Rb = Epi::PERM ? ((R & ~31) + perm32(R & 31)) : R;
;         voffA[i] = (unsigned)(R * K + C) * 2u; voffB[i] = (unsigned)(Rb * K + C) * 2u; }
;     const size_t kstep = (size_t)(BK * 2);
;     const size_t hstep = (size_t)HALF * K * 2;
;     const size_t tstep = 2 * hstep;
;     const unsigned ldsw = (unsigned)wid * 1024u;
;     const int aoff = lds_byte(wr * 64 + fr, fq * 8), boff = lds_byte(wc * 32 + fr, fq * 8);
;     ...
;     Unit cur, nxt; int ui = 0;
;     if (!S.next(0, cur)) return;
;     f32x4 acc[2][2][4][2];
; #pragma unroll
;     for (int a = 0; a < 2; ++a)
; #pragma unroll
;         for (int b = 0; b < 2; ++b)
; #pragma unroll
;             for (int m = 0; m < 4; ++m)
; #pragma unroll
;                 for (int n = 0; n < 2; ++n) acc[a][b][m][n] = (f32x4){0.f, 0.f, 0.f, 0.f};
;     bf16x8 At[4][2], B0[2][2], B1[2][2];
;     const char* cA = (const char*)g.A + (size_t)cur.pm * tstep; const char* cB = (const char*)g.Bt + (size_t)cur.pn * tstep;
;     PG8_STAGE(PG8_SB(0, 0), cB, voffB); PG8_STAGE(PG8_SA(0, 0), cA, voffA); PG8_STAGE(PG8_SB(0, 1), cB + hstep, voffB); PG8_STAGE(PG8_SA(0, 1), cA + hstep, voffA);
;     if (wr == 1) PG8_BAR;
;     PG8_WAIT_V(4); PG8_BAR;
;     PG8_STAGE(PG8_SB(1, 0), cB + kstep, voffB); PG8_STAGE(PG8_SA(1, 0), cA + kstep, voffA); PG8_STAGE(PG8_SB(1, 1), cB + hstep + kstep, voffB);
;     PG8_WAIT_V(6); PG8_BAR;
.Lstag9_done:
	s_add_u32 s6, s12, 0xebc2000
	s_addc_u32 s7, s13, 0
	v_lshrrev_b32_e32 v144, 3, v214
	v_and_b32_e32 v146, 15, v214
	s_cmpk_gt_i32 s94, 0x5ab
	v_lshrrev_b32_e32 v145, 4, v214
	s_movk_i32 s0, 0x60
	v_readfirstlane_b32 s28, v214
	s_cbranch_scc1 .LBB0_1155
	v_lshrrev_b32_e32 v2, 1, v214
	v_and_b32_e32 v11, 24, v2
	v_lshrrev_b32_e32 v2, 5, v214
	v_lshlrev_b32_e32 v0, 4, v214
	v_and_b32_e32 v1, 32, v214
	v_and_b32_e32 v2, 4, v2
	v_bfe_u32 v3, v214, 2, 2
	v_bfe_u32 v10, v214, 2, 4
	v_bitop3_b32 v8, v0, v1, 48 bitop3:0x6c
	v_and_b32_e32 v9, 64, v214
	v_or3_b32 v2, v2, v3, v11
	s_movk_i32 s1, 0x70
	v_add_u32_e32 v12, 0x2000, v0
	v_or_b32_e32 v1, v8, v9
	v_and_or_b32 v3, v144, s1, v10
	v_and_or_b32 v4, v144, s0, v2
	v_lshrrev_b32_e32 v0, 7, v12
	s_movk_i32 s0, 0xf0
	v_lshl_or_b32 v128, v3, 12, v1
	v_and_or_b32 v3, v0, s0, v10
	s_movk_i32 s0, 0xe0
	v_and_or_b32 v0, v0, s0, v2
	s_mul_hi_i32 s0, s94, 0xb48a39d5
	s_add_i32 s0, s0, s94
	s_lshr_b32 s1, s0, 31
	s_ashr_i32 s0, s0, 10
	s_add_i32 s0, s0, s1
	s_mulk_i32 s0, 0x5ac
	s_sub_i32 s0, s94, s0
	s_bfe_u32 s1, s0, 0x3001c
	s_add_i32 s1, s0, s1
	s_sext_i32_i16 s2, s1
	s_and_b32 s1, s1, 0xfff8
	s_sub_i32 s0, s0, s1
	s_lshr_b32 s4, s28, 6
	s_mul_i32 s5, s0, 0xb5
	s_lshr_b32 s3, s28, 8
	s_lshl_b32 s29, s4, 10
	s_ashr_i32 s2, s2, 3
	s_mul_i32 s1, s0, 0xb6
	s_add_i32 s5, s5, 4
	s_sext_i32_i16 s0, s0
	s_cmp_lt_i32 s0, 4
	s_cselect_b32 s0, s1, s5
	s_add_i32 s0, s0, s2
	s_sext_i32_i16 s1, s0
	s_mulk_i32 s1, 0xba3
	s_lshr_b32 s2, s1, 31
	s_ashr_i32 s1, s1, 20
	s_add_i32 s1, s1, s2
	s_lshl_b32 s5, s1, 3
	s_sub_i32 s2, 33, s5
	s_mulk_i32 s1, 0x160
	s_min_u32 s8, s2, 8
	s_sub_i32 s9, s0, s1
	v_lshl_or_b32 v132, v3, 12, v1
	s_sext_i32_i16 s0, s9
	v_cvt_f32_ubyte0_e32 v3, s8
	v_lshl_or_b32 v130, v4, 12, v1
	v_cvt_f32_i32_e32 v2, s0
	v_rcp_iflag_f32_e32 v4, v3
	v_lshl_or_b32 v134, v0, 12, v1
	s_ashr_i32 s0, s0, 30
	s_or_b32 s2, s0, 1
	v_mul_f32_e32 v0, v2, v4
	v_trunc_f32_e32 v0, v0
	v_fma_f32 v1, -v0, v3, v2
	v_cvt_i32_f32_e32 v0, v0
	v_cmp_ge_f32_e64 s[0:1], |v1|, v3
	s_and_b64 s[0:1], s[0:1], exec
	s_cselect_b32 s0, s2, 0
	v_readfirstlane_b32 s1, v0
	s_add_i32 s2, s1, s0
	s_mul_i32 s0, s2, s8
	s_sub_i32 s0, s9, s0
	s_sext_i32_i16 s0, s0
	s_add_i32 s20, s5, s0
	s_ashr_i32 s21, s20, 31
	s_bfe_i64 s[8:9], s[2:3], 0x100000
	s_lshl_b64 s[0:1], s[20:21], 20
	s_lshl_b64 s[8:9], s[8:9], 20
	s_add_u32 s24, s6, s8
	s_addc_u32 s25, s7, s9
	s_add_i32 s21, s29, 0
	s_add_i32 m0, s21, 0x10000
	v_mov_b32_e32 v131, 0
	global_load_lds_dwordx4 v130, s[24:25]
	s_add_i32 m0, s21, 0x12000
	s_add_u32 s22, s12, s0
	global_load_lds_dwordx4 v134, s[24:25]
	s_addc_u32 s23, s13, s1
	s_mov_b32 m0, s21
	s_add_i32 s30, s21, 0x2000
	global_load_lds_dwordx4 v128, s[22:23]
	s_mov_b32 m0, s30
	s_add_u32 s0, s24, 0x80000
	global_load_lds_dwordx4 v132, s[22:23]
	s_addc_u32 s1, s25, 0
	s_add_i32 m0, s21, 0x14000
	v_mov_b32_e32 v135, v131
	global_load_lds_dwordx4 v130, s[0:1]
	s_add_i32 m0, s21, 0x16000
	v_mov_b32_e32 v129, v131
	global_load_lds_dwordx4 v134, s[0:1]
	s_add_u32 s0, s22, 0x80000
	s_addc_u32 s1, s23, 0
	s_add_i32 s31, s21, 0x4000
	s_mov_b32 m0, s31
	s_add_i32 s33, s21, 0x6000
	global_load_lds_dwordx4 v128, s[0:1]
	s_mov_b32 m0, s33
	v_mov_b32_e32 v133, v131
	global_load_lds_dwordx4 v132, s[0:1]
	s_mov_b32 s34, 0
	v_lshl_add_u64 v[6:7], s[24:25], 0, v[130:131]
	v_lshl_add_u64 v[4:5], s[24:25], 0, v[134:135]
	v_lshl_add_u64 v[2:3], s[22:23], 0, v[128:129]
	s_cmp_lg_u32 s3, 1
	v_lshl_add_u64 v[0:1], s[22:23], 0, v[132:133]
	s_cbranch_scc1 .LBB0_1142
	s_barrier
